# speedup vs baseline: 1.0263x; 1.0263x over previous
; __device__ void quant_rows_fp4(const float* __restrict__ src, unsigned char* __restrict__ dst, int rows) {
;   const int lane = otid() & 63, w = otid() >> 6;
;   for (int row = blockIdx.x * 8 + w; row < rows; row += gridDim.x * 8) {
;     const float* sp = src + (long)row * D_ + lane * 32;
;     pg_f32x4 v[8];
;     float am = 0.f;
; #pragma unroll
;     for (int i = 0; i < 8; ++i) {
;       v[i] = *(const pg_f32x4*)(sp + 4 * i);
;       am = fmaxf(am, fmaxf(fmaxf(fabsf(v[i][0]), fabsf(v[i][1])), fmaxf(fabsf(v[i][2]), fabsf(v[i][3]))));
;     }
;     int eb = (int)((__float_as_uint(am * (1.f / 6.f)) >> 23) & 0xFF);
;     if ((__float_as_uint(am * (1.f / 6.f)) & 0x7FFFFFu) != 0u) eb += 1;
;     eb = min(max(eb, 1), 254);
;     const float inv = __uint_as_float((unsigned)(254 - eb) << 23);
;     u32x4 o;
; #pragma unroll
;     for (int k = 0; k < 4; ++k) {
;       float e[8] = {v[2 * k][0], v[2 * k][1], v[2 * k][2], v[2 * k][3], v[2 * k + 1][0], v[2 * k + 1][1], v[2 * k + 1][2], v[2 * k + 1][3]};
;       unsigned wd = 0;
; #pragma unroll
;       for (int n = 0; n < 8; ++n) {
;         float a = fabsf(e[n]) * inv;
;         unsigned code = (a < 0.25f) ? 0u : (a < 0.75f) ? 1u : (a < 1.25f) ? 2u : (a < 1.75f) ? 3u : (a < 2.5f) ? 4u : (a < 3.5f) ? 5u : (a < 5.0f) ? 6u : 7u;
;         code |= (e[n] < 0.f) ? 8u : 0u;
;         wd |= code << (4 * n);
;       }
;       o[k] = wd;
;     }
;     unsigned char* rp = dst + (long)row * UROW;
;     *(u32x4*)(rp + lane * 16) = o;
;     rp[1024 + lane] = (unsigned char)eb;
;   }
; }
; __device__ void quant_rows_fp6(const float* __restrict__ src, unsigned char* __restrict__ dst, int rows) {
;   const int lane = otid() & 63, w = otid() >> 6;
;   for (int row = blockIdx.x * 8 + w; row < rows; row += gridDim.x * 8) {
;     const float* sp = src + (long)row * D_ + lane * 32;
;     pg_f32x4 v[8];
;     float am = 0.f;
; #pragma unroll
;     for (int i = 0; i < 8; ++i) {
;       v[i] = *(const pg_f32x4*)(sp + 4 * i);
;       am = fmaxf(am, fmaxf(fmaxf(fabsf(v[i][0]), fabsf(v[i][1])), fmaxf(fabsf(v[i][2]), fabsf(v[i][3]))));
;     }
;     const float amq = am * (1.f / 7.5f);
;     int eb = (int)((__float_as_uint(amq) >> 23) & 0xFF);
;     if ((__float_as_uint(amq) & 0x7FFFFFu) != 0u) eb += 1;
;     eb = min(max(eb, 1), 254);
;     const float inv = __uint_as_float((unsigned)(254 - eb) << 23);
.LBB0_16:
	v_ashrrev_i32_e32 v35, 31, v34
	v_lshlrev_b64 v[2:3], 13, v[34:35]
	v_lshl_add_u64 v[64:65], v[40:41], 0, v[2:3]
	global_load_dwordx4 v[2:5], v[64:65], off
	global_load_dwordx4 v[6:9], v[64:65], off offset:16
	global_load_dwordx4 v[10:13], v[64:65], off offset:32
	global_load_dwordx4 v[14:17], v[64:65], off offset:48
	global_load_dwordx4 v[18:21], v[64:65], off offset:64
	global_load_dwordx4 v[22:25], v[64:65], off offset:80
	global_load_dwordx4 v[26:29], v[64:65], off offset:96
	global_load_dwordx4 v[30:33], v[64:65], off offset:112
	s_waitcnt vmcnt(0)
	v_max3_f32 v35, |v2|, |v3|, |v4|
	v_max3_f32 v35, v35, |v5|, |v6|
	v_max3_f32 v35, v35, |v7|, |v8|
	v_max3_f32 v35, v35, |v9|, |v10|
	v_max3_f32 v35, v35, |v11|, |v12|
	v_max3_f32 v35, v35, |v13|, |v14|
	v_max3_f32 v35, v35, |v15|, |v16|
	v_max3_f32 v35, v35, |v17|, |v18|
	v_max3_f32 v35, v35, |v19|, |v20|
	v_max3_f32 v35, v35, |v21|, |v22|
	v_max3_f32 v35, v35, |v23|, |v24|
	v_max3_f32 v35, v35, |v25|, |v26|
	v_max3_f32 v35, v35, |v27|, |v28|
	v_max3_f32 v35, v35, |v29|, |v30|
	v_max3_f32 v35, v35, |v31|, |v32|
	v_max_f32_e64 v35, v35, |v33|
	v_mul_f32_e32 v35, 0x3e2aaaab, v35
	v_bfe_u32 v63, v35, 23, 8
	v_and_b32_e32 v35, 0x7fffff, v35
	v_cmp_ne_u32_e32 vcc, 0, v35
	s_nop 1
	v_addc_co_u32_e32 v35, vcc, 0, v63, vcc
	v_med3_u32 v35, v35, 1, v1
	v_lshlrev_b32_e32 v63, 23, v35
	s_nop 1
	v_cvt_scalef32_pk_fp4_f32 v66, v2, v3, v63
	s_nop 0
	v_cvt_scalef32_pk_fp4_f32 v66, v4, v5, v63 op_sel:[0,0,1,0]
	s_nop 0
	v_cvt_scalef32_pk_fp4_f32 v66, v6, v7, v63 op_sel:[0,0,0,1]
	s_nop 0
	v_cvt_scalef32_pk_fp4_f32 v66, v8, v9, v63 op_sel:[0,0,1,1]
	s_nop 0
	v_cvt_scalef32_pk_fp4_f32 v67, v10, v11, v63
	s_nop 0
	v_cvt_scalef32_pk_fp4_f32 v67, v12, v13, v63 op_sel:[0,0,1,0]
	s_nop 0
	v_cvt_scalef32_pk_fp4_f32 v67, v14, v15, v63 op_sel:[0,0,0,1]
	s_nop 0
	v_cvt_scalef32_pk_fp4_f32 v67, v16, v17, v63 op_sel:[0,0,1,1]
	s_nop 0
	v_cvt_scalef32_pk_fp4_f32 v68, v18, v19, v63
	s_nop 0
	v_cvt_scalef32_pk_fp4_f32 v68, v20, v21, v63 op_sel:[0,0,1,0]
	s_nop 0
	v_cvt_scalef32_pk_fp4_f32 v68, v22, v23, v63 op_sel:[0,0,0,1]
	s_nop 0
	v_cvt_scalef32_pk_fp4_f32 v68, v24, v25, v63 op_sel:[0,0,1,1]
	s_nop 0
	v_cvt_scalef32_pk_fp4_f32 v69, v26, v27, v63
	s_nop 0
	v_cvt_scalef32_pk_fp4_f32 v69, v28, v29, v63 op_sel:[0,0,1,0]
	s_nop 0
	v_cvt_scalef32_pk_fp4_f32 v69, v30, v31, v63 op_sel:[0,0,0,1]
	s_nop 0
	v_cvt_scalef32_pk_fp4_f32 v69, v32, v33, v63 op_sel:[0,0,1,1]
	s_nop 0
	v_mov_b64_e32 v[6:7], s[16:17]
	s_movk_i32 s10, 0xa80
	v_mad_i64_i32 v[6:7], s[10:11], v34, s10, v[6:7]
	v_add_u32_e32 v34, s33, v34
	s_movk_i32 s10, 0x7fff
	v_lshl_add_u64 v[8:9], v[6:7], 0, v[38:39]
	v_cmp_lt_i32_e32 vcc, s10, v34
	global_store_dwordx4 v[8:9], v[66:69], off
	s_or_b64 s[8:9], vcc, s[8:9]
	s_nop 0
	v_lshl_add_u64 v[2:3], v[6:7], 0, v[36:37]
	global_store_byte v[2:3], v35, off offset:1024
	s_andn2_b64 exec, exec, s[8:9]
	s_cbranch_execz .LBB0_395
	s_branch .LBB0_16
.LBB0_395:
	s_or_b64 exec, exec, s[0:1]
	v_mov_b32_e32 v1, v207
	v_mov_b32_e32 v2, v207
	v_readlane_b32 s0, v252, 40
	v_ashrrev_i32_e32 v2, 6, v2
	s_nop 0
	v_add_u32_e32 v34, s0, v2
	s_mov_b32 s0, 0x8000
	v_cmp_gt_i32_e32 vcc, s0, v34
	s_and_saveexec_b64 s[0:1], vcc
	s_cbranch_execz .LBB0_782
	v_and_b32_e32 v36, 63, v1
	v_readlane_b32 s76, v252, 24
	v_lshlrev_b32_e32 v38, 7, v36
	v_mov_b32_e32 v39, 0
	v_readlane_b32 s84, v252, 32
	v_readlane_b32 s85, v252, 33
	v_mov_b32_e32 v37, v39
	s_lshl_b32 s30, s94, 3
	v_lshl_add_u64 v[40:41], s[84:85], 0, v[38:39]
	v_lshlrev_b32_e32 v38, 3, v36
	s_mov_b64 s[8:9], 0
	v_mov_b32_e32 v1, 0xfe
	s_movk_i32 s31, 0xa80
	s_movk_i32 s33, 0x7fff
	v_readlane_b32 s77, v252, 25
	v_readlane_b32 s78, v252, 26
	v_readlane_b32 s79, v252, 27
	v_readlane_b32 s80, v252, 28
	v_readlane_b32 s81, v252, 29
	v_readlane_b32 s82, v252, 30
	v_readlane_b32 s83, v252, 31
	v_readlane_b32 s86, v252, 34
	v_readlane_b32 s87, v252, 35
	v_readlane_b32 s88, v252, 36
	v_readlane_b32 s89, v252, 37
	v_readlane_b32 s90, v252, 38
	v_readlane_b32 s91, v252, 39
	s_branch .LBB0_398
.LBB0_398:
	v_ashrrev_i32_e32 v35, 31, v34
	v_lshlrev_b64 v[2:3], 13, v[34:35]
	v_lshl_add_u64 v[42:43], v[40:41], 0, v[2:3]
	global_load_dwordx4 v[2:5], v[42:43], off
	global_load_dwordx4 v[6:9], v[42:43], off offset:16
	global_load_dwordx4 v[10:13], v[42:43], off offset:32
	global_load_dwordx4 v[14:17], v[42:43], off offset:48
	global_load_dwordx4 v[18:21], v[42:43], off offset:64
	global_load_dwordx4 v[22:25], v[42:43], off offset:80
	global_load_dwordx4 v[26:29], v[42:43], off offset:96
	global_load_dwordx4 v[30:33], v[42:43], off offset:112
	s_waitcnt vmcnt(0)
	v_max3_f32 v35, |v2|, |v3|, |v4|
	v_max3_f32 v35, v35, |v5|, |v6|
	v_max3_f32 v35, v35, |v7|, |v8|
	v_max3_f32 v35, v35, |v9|, |v10|
	v_max3_f32 v35, v35, |v11|, |v12|
	v_max3_f32 v35, v35, |v13|, |v14|
	v_max3_f32 v35, v35, |v15|, |v16|
	v_max3_f32 v35, v35, |v17|, |v18|
	v_max3_f32 v35, v35, |v19|, |v20|
	v_max3_f32 v35, v35, |v21|, |v22|
	v_max3_f32 v35, v35, |v23|, |v24|
	v_max3_f32 v35, v35, |v25|, |v26|
	v_max3_f32 v35, v35, |v27|, |v28|
	v_max3_f32 v35, v35, |v29|, |v30|
	v_max3_f32 v35, v35, |v31|, |v32|
	v_max_f32_e64 v35, v35, |v33|
	v_mul_f32_e32 v35, 0x3e088889, v35
	v_bfe_u32 v74, v35, 23, 8
	v_and_b32_e32 v35, 0x7fffff, v35
	v_cmp_ne_u32_e32 vcc, 0, v35
	s_nop 1
	v_addc_co_u32_e32 v35, vcc, 0, v74, vcc
	v_med3_u32 v35, v35, 1, v1
	v_lshlrev_b32_e32 v74, 23, v35
	v_mov_b32_e32 v42, v2
	v_mov_b32_e32 v58, v3
	v_mov_b32_e32 v43, v4
	v_mov_b32_e32 v59, v5
	v_mov_b32_e32 v44, v6
	v_mov_b32_e32 v60, v7
	v_mov_b32_e32 v45, v8
	v_mov_b32_e32 v61, v9
	v_mov_b32_e32 v46, v10
	v_mov_b32_e32 v62, v11
	v_mov_b32_e32 v47, v12
	v_mov_b32_e32 v63, v13
	v_mov_b32_e32 v48, v14
	v_mov_b32_e32 v64, v15
	v_mov_b32_e32 v49, v16
	v_mov_b32_e32 v65, v17
	v_mov_b32_e32 v50, v18
	v_mov_b32_e32 v66, v19
	v_mov_b32_e32 v51, v20
	v_mov_b32_e32 v67, v21
	v_mov_b32_e32 v52, v22
	v_mov_b32_e32 v68, v23
	v_mov_b32_e32 v53, v24
	v_mov_b32_e32 v69, v25
	v_mov_b32_e32 v54, v26
	v_mov_b32_e32 v70, v27
	v_mov_b32_e32 v55, v28
	v_mov_b32_e32 v71, v29
	v_mov_b32_e32 v56, v30
	v_mov_b32_e32 v72, v31
	v_mov_b32_e32 v57, v32
	v_mov_b32_e32 v73, v33
	s_nop 1
	v_cvt_scalef32_2xpk16_fp6_f32 v[2:7], v[42:57], v[58:73], v74
	v_mov_b64_e32 v[8:9], s[16:17]
	v_mad_i64_i32 v[8:9], s[10:11], v34, s31, v[8:9]
	v_add_u32_e32 v34, s30, v34
	v_lshl_add_u64 v[10:11], v[8:9], 0, v[38:39]
	v_cmp_lt_i32_e32 vcc, s33, v34
	global_store_dwordx2 v[10:11], v[2:3], off offset:1088
	global_store_dwordx2 v[10:11], v[4:5], off offset:1600
	global_store_dwordx2 v[10:11], v[6:7], off offset:2112
	v_lshl_add_u64 v[12:13], v[8:9], 0, v[36:37]
	s_or_b64 s[8:9], vcc, s[8:9]
	global_store_byte v[12:13], v35, off offset:2624
	s_andn2_b64 exec, exec, s[8:9]
	s_cbranch_execz .LBB0_782
	s_branch .LBB0_398

; __device__ __forceinline__ unsigned pack2(float a, float b) { return (unsigned)f2bf(a) | ((unsigned)f2bf(b) << 16); }
; __device__ void phase_peer(const Params& p, int l, float* xout, char* smem) {
;     ...
;   const unsigned char* Ub = p.Ub + (long)l * 16384 * UROW;
;   const unsigned char* Vb = p.Vb + (long)l * 16384 * VROW;
;   const float* g2 = p.ln2_g + l * D_;
;   const float* b2 = p.ln2_b + l * D_;
;   for (int t = blockIdx.x * 8 + w; t < S_; t += gridDim.x * 8) {
;     ...
;       if (xout) {
;         float* op = xout + (long)t * D_ + c0;
;         *(float4*)op = make_float4(o[0], o[1], o[2], o[3]);
;         *(float4*)(op + 4) = make_float4(o[4], o[5], o[6], o[7]);
;       }
;       uint4 pk; pk.x = pack2(o[0], o[1]); pk.y = pack2(o[2], o[3]); pk.z = pack2(o[4], o[5]); pk.w = pack2(o[6], o[7]);
;       *(uint4*)(p.xb + (long)t * D_ + c0) = pk;
;     }
;   }
.LBB0_1255:
	s_or_b64 exec, exec, s[0:1]
	s_waitcnt lgkmcnt(0)
	v_mov_b32_e32 v0, v207
	v_mov_b32_e32 v1, v207
	s_barrier
	v_readlane_b32 s0, v252, 40
	v_ashrrev_i32_e32 v1, 6, v1
	s_nop 0
	v_add_u32_e32 v72, s0, v1
	v_cmp_gt_i32_e32 vcc, s83, v72
	s_and_saveexec_b64 s[0:1], vcc
	s_movk_i32 s78, 0x3fff
	s_cbranch_execz .LBB0_1270
	v_readlane_b32 s2, v250, 10
	s_lshl_b32 s2, s2, 14
	s_mul_i32 s3, s2, 0xa80
	v_readlane_b32 s16, v252, 0
	v_readlane_b32 s17, v252, 1
	s_add_u32 s42, s16, s3
	v_readlane_b32 s18, v252, 2
	s_addc_u32 s43, s17, 0
	s_mulk_i32 s2, 0x640
	v_readlane_b32 s19, v252, 3
	v_readlane_b32 s20, v252, 4
	v_readlane_b32 s21, v252, 5
	v_readlane_b32 s22, v252, 6
	v_readlane_b32 s23, v252, 7
	s_add_u32 s90, s42, 0x440
	s_addc_u32 s91, s43, 0
	v_readlane_b32 s16, v252, 24
	s_lshl_b64 s[2:3], s[6:7], 2
	v_readlane_b32 s28, v252, 36
	v_readlane_b32 s29, v252, 37
	s_add_u32 s40, s28, s2
	v_readlane_b32 s20, v252, 28
	v_readlane_b32 s21, v252, 29
	v_readlane_b32 s26, v252, 34
	s_addc_u32 s41, s29, s3
	v_readlane_b32 s17, v252, 25
	v_readlane_b32 s18, v252, 26
	v_readlane_b32 s19, v252, 27
	v_readlane_b32 s27, v252, 35
	v_readlane_b32 s20, v251, 54
	s_add_u32 s66, s26, s2
	v_and_b32_e32 v74, 63, v0
	v_lshlrev_b32_e32 v3, 5, v0
	v_lshlrev_b32_e32 v2, 10, v1
	v_readlane_b32 s21, v251, 55
	s_addc_u32 s67, s27, s3
	v_and_b32_e32 v198, 0x60, v3
	v_and_b32_e32 v3, 4, v0
	s_movk_i32 s4, 0x1500
	v_lshlrev_b32_e32 v176, 7, v74
	v_readlane_b32 s16, v250, 6
	v_add_u32_e32 v79, 16, v2
	v_cmp_eq_u32_e64 s[2:3], 0, v3
	v_mul_lo_u32 v1, v1, s4
	v_lshlrev_b32_e32 v3, 2, v74
	v_bfe_u32 v78, v0, 2, 1
	v_and_b32_e32 v0, 7, v0
	s_cmp_lg_u64 s[20:21], 0
	v_lshl_add_u64 v[80:81], s[66:67], 0, v[176:177]
	v_lshl_add_u64 v[82:83], s[40:41], 0, v[176:177]
	v_lshlrev_b32_e32 v176, 6, v74
	v_readlane_b32 s17, v250, 7
	v_lshlrev_b32_e32 v76, 5, v74
	v_add3_u32 v199, v79, v1, v3
	v_cmp_eq_u32_e64 s[38:39], 0, v0
	v_mov_b32_e32 v75, v177
	s_mov_b64 s[86:87], 0
	s_cselect_b64 s[88:89], -1, 0
	v_lshl_add_u32 v200, v74, 3, v79
	v_lshl_add_u64 v[84:85], s[36:37], 0, v[176:177]
	v_lshl_add_u64 v[86:87], s[16:17], 0, v[176:177]
	v_mov_b32_e32 v77, v78
	v_lshl_add_u64 v[88:89], s[54:55], 0, v[176:177]
	v_add3_u32 v201, 16, 8, v2
	v_readlane_b32 s22, v252, 30
	v_readlane_b32 s23, v252, 31
	v_readlane_b32 s24, v252, 32
	v_readlane_b32 s25, v252, 33
	v_readlane_b32 s30, v252, 38
	v_readlane_b32 s31, v252, 39
	v_readlane_b32 s18, v250, 8
	v_readlane_b32 s19, v250, 9
	s_branch .LBB0_1258
.LBB0_1257:
	v_and_b32_sdwa v8, v11, v209 dst_sel:DWORD dst_unused:UNUSED_PAD src0_sel:WORD_1 src1_sel:DWORD
	v_and_b32_sdwa v9, v10, v209 dst_sel:DWORD dst_unused:UNUSED_PAD src0_sel:WORD_1 src1_sel:DWORD
	v_and_b32_sdwa v0, v13, v209 dst_sel:DWORD dst_unused:UNUSED_PAD src0_sel:WORD_1 src1_sel:DWORD
	v_and_b32_sdwa v1, v12, v209 dst_sel:DWORD dst_unused:UNUSED_PAD src0_sel:WORD_1 src1_sel:DWORD
	v_add3_u32 v8, v11, v8, s65
	v_add3_u32 v9, v10, v9, s65
	v_add3_u32 v1, v12, v1, s65
	v_add3_u32 v0, v13, v0, s65
	v_and_b32_e32 v8, 0xffff0000, v8
	v_and_b32_e32 v10, 0xffff0000, v9
	v_or_b32_sdwa v9, v8, v0 dst_sel:DWORD dst_unused:UNUSED_PAD src0_sel:DWORD src1_sel:WORD_1
	v_or_b32_sdwa v8, v10, v1 dst_sel:DWORD dst_unused:UNUSED_PAD src0_sel:DWORD src1_sel:WORD_1
	v_and_b32_sdwa v0, v7, v209 dst_sel:DWORD dst_unused:UNUSED_PAD src0_sel:WORD_1 src1_sel:DWORD
	v_and_b32_sdwa v1, v6, v209 dst_sel:DWORD dst_unused:UNUSED_PAD src0_sel:WORD_1 src1_sel:DWORD
	v_add3_u32 v1, v6, v1, s65
	v_add3_u32 v0, v7, v0, s65
	v_and_b32_sdwa v6, v5, v209 dst_sel:DWORD dst_unused:UNUSED_PAD src0_sel:WORD_1 src1_sel:DWORD
	v_and_b32_sdwa v7, v4, v209 dst_sel:DWORD dst_unused:UNUSED_PAD src0_sel:WORD_1 src1_sel:DWORD
	v_add3_u32 v5, v5, v6, s65
	v_add3_u32 v4, v4, v7, s65
	v_readfirstlane_b32 s100, v253
	s_nop 0
	v_mov_b32_e32 v72, s100
	v_and_b32_e32 v72, 0x3fff, v72
	v_add_u32_e32 v72, s82, v72
	v_and_b32_e32 v5, 0xffff0000, v5
	v_and_b32_e32 v4, 0xffff0000, v4
	v_cmp_lt_i32_e32 vcc, s78, v72
	v_or_b32_sdwa v11, v5, v0 dst_sel:DWORD dst_unused:UNUSED_PAD src0_sel:DWORD src1_sel:WORD_1
	v_or_b32_sdwa v10, v4, v1 dst_sel:DWORD dst_unused:UNUSED_PAD src0_sel:DWORD src1_sel:WORD_1
	s_or_b64 s[86:87], vcc, s[86:87]
	global_store_dwordx4 v[2:3], v[8:11], off offset:48
	s_andn2_b64 exec, exec, s[86:87]
	s_cbranch_execz .LBB0_1270

; __device__ __forceinline__ float bflo(unsigned u) { return __uint_as_float(u << 16); }
; __device__ __forceinline__ float bfhi(unsigned u) { return __uint_as_float(u & 0xffff0000u); }
; __device__ void phase_peer(const Params& p, int l, float* xout, char* smem) {
;     ...
;     f32x2 xf2[16];
; #pragma unroll
;     for (int i = 0; i < 4; ++i) {
;       unsigned uu[4] = {xraw[i][0], xraw[i][1], xraw[i][2], xraw[i][3]};
; #pragma unroll
;       for (int j = 0; j < 4; ++j) { xf2[i * 4 + j][0] = bflo(uu[j]); xf2[i * 4 + j][1] = bfhi(uu[j]); }
;     }
;     f32x2 acc2[16];
; #pragma unroll
;     for (int j = 0; j < 16; ++j) acc2[j] = (f32x2){0.f, 0.f};
;     if ((lane & 7) == 0) {
; #pragma unroll
;       for (int k = 0; k < 16; ++k) { sel_e[(lane >> 3) * 16 + k] = ex[k]; sel_g[(lane >> 3) * 16 + k] = gate[k]; }
;     }
;     ...
;     {
;       u32x4 uA[PB], uB[PB]; u32x2 vA[PB][3], vB[PB][3];
;       unsigned char suA[PB], suB[PB], svA[PB], svB[PB];
;       float gA[PB], gB[PB];
;       PEER_LOAD(uA, vA, suA, svA, gA, 0);
.LBB0_1260:
	s_or_b64 exec, exec, s[40:41]
	s_waitcnt vmcnt(0)
	v_lshlrev_b32_e32 v93, 16, v13
	v_lshlrev_b32_e32 v92, 16, v12
	v_and_b32_e32 v95, 0xffff0000, v13
	v_and_b32_e32 v94, 0xffff0000, v12
	v_lshlrev_b32_e32 v97, 16, v15
	v_lshlrev_b32_e32 v96, 16, v14
	v_and_b32_e32 v99, 0xffff0000, v15
	v_and_b32_e32 v98, 0xffff0000, v14
	ds_read2st64_b64 v[12:15], v79 offset1:1
	v_lshlrev_b64 v[90:91], 11, v[72:73]
	v_lshlrev_b32_e32 v101, 16, v9
	v_lshlrev_b32_e32 v100, 16, v8
	v_and_b32_e32 v109, 0xffff0000, v9
	s_waitcnt lgkmcnt(0)
	v_readfirstlane_b32 s4, v12
	s_mul_i32 s11, s4, 0xa80
	s_mul_hi_i32 s5, s4, 0xa80
	s_add_u32 s40, s42, s11
	s_addc_u32 s41, s43, s5
	s_mul_hi_i32 s5, s4, 0xa80
	s_mulk_i32 s4, 0xa80
	s_add_u32 s66, s90, s4
	v_readfirstlane_b32 s4, v13
	v_and_b32_e32 v108, 0xffff0000, v8
	s_addc_u32 s67, s91, s5
	v_lshlrev_b32_e32 v73, 4, v74
	v_lshl_add_u64 v[8:9], s[40:41], 0, v[74:75]
	s_mul_i32 s11, s4, 0xa80
	global_load_dwordx4 v[56:59], v73, s[40:41]
	global_load_ubyte v205, v[8:9], off offset:1024
	s_mul_hi_i32 s5, s4, 0xa80
	s_add_u32 s40, s42, s11
	v_lshlrev_b32_e32 v176, 3, v74
	v_lshl_add_u64 v[8:9], s[66:67], 0, v[74:75]
	s_addc_u32 s41, s43, s5
	s_mul_hi_i32 s5, s4, 0xa80
	s_mulk_i32 s4, 0xa80
	global_load_dwordx2 v[32:33], v176, s[66:67]
	global_load_dwordx2 v[34:35], v176, s[66:67] offset:512
	global_load_dwordx2 v[36:37], v176, s[66:67] offset:1024
	global_load_ubyte v203, v[8:9], off offset:1536
	s_add_u32 s66, s90, s4
	v_lshl_add_u64 v[8:9], s[40:41], 0, v[74:75]
	s_addc_u32 s67, s91, s5
	global_load_dwordx4 v[60:63], v73, s[40:41]
	global_load_ubyte v206, v[8:9], off offset:1024
	global_load_dwordx2 v[38:39], v176, s[66:67]
	global_load_dwordx2 v[40:41], v176, s[66:67] offset:512
	global_load_dwordx2 v[42:43], v176, s[66:67] offset:1024
	v_lshl_add_u64 v[8:9], s[66:67], 0, v[74:75]
	global_load_ubyte v204, v[8:9], off offset:1536
	v_lshlrev_b32_e32 v113, 16, v11
	v_lshlrev_b32_e32 v112, 16, v10
	v_and_b32_e32 v115, 0xffff0000, v11
	v_and_b32_e32 v114, 0xffff0000, v10
	v_lshlrev_b32_e32 v117, 16, v5
	v_lshlrev_b32_e32 v116, 16, v4
	v_and_b32_e32 v119, 0xffff0000, v5
	v_and_b32_e32 v118, 0xffff0000, v4
	v_lshlrev_b32_e32 v121, 16, v7
	v_lshlrev_b32_e32 v120, 16, v6
	v_and_b32_e32 v123, 0xffff0000, v7
	v_and_b32_e32 v122, 0xffff0000, v6
	v_lshlrev_b32_e32 v125, 16, v1
	v_lshlrev_b32_e32 v124, 16, v0
	v_and_b32_e32 v127, 0xffff0000, v1
	v_and_b32_e32 v126, 0xffff0000, v0
	v_lshlrev_b32_e32 v131, 16, v3
	v_lshlrev_b32_e32 v130, 16, v2
	v_and_b32_e32 v133, 0xffff0000, v3
	v_and_b32_e32 v132, 0xffff0000, v2
	v_mov_b32_e32 v156, 0
	v_mov_b32_e32 v102, v92
	v_mov_b32_e32 v103, v94
	v_mov_b32_e32 v104, v93
	v_mov_b32_e32 v105, v95
	v_mov_b32_e32 v106, v96
	v_mov_b32_e32 v107, v98
	v_mov_b32_e32 v110, v97
	v_mov_b32_e32 v111, v99
	v_mov_b32_e32 v128, v100
	v_mov_b32_e32 v129, v108
	v_mov_b32_e32 v134, v101
	v_mov_b32_e32 v135, v109
	v_mov_b32_e32 v136, v112
	v_mov_b32_e32 v137, v114
	v_mov_b32_e32 v138, v113
	v_mov_b32_e32 v139, v115
	v_mov_b32_e32 v140, v116
	v_mov_b32_e32 v141, v118
	v_mov_b32_e32 v142, v117
	v_mov_b32_e32 v143, v119
	v_mov_b32_e32 v144, v120
	v_mov_b32_e32 v145, v122
	v_mov_b32_e32 v146, v121
	v_mov_b32_e32 v147, v123
	v_mov_b32_e32 v148, v124
	v_mov_b32_e32 v149, v126
	v_mov_b32_e32 v150, v125
	v_mov_b32_e32 v151, v127
	v_mov_b32_e32 v152, v130
	v_mov_b32_e32 v153, v132
	v_mov_b32_e32 v154, v131
	v_mov_b32_e32 v155, v133
	v_readfirstlane_b32 s40, v14
	v_readfirstlane_b32 s11, v15
	s_mov_b32 s66, -4
	v_mov_b32_e32 v202, v201
	v_mov_b32_e32 v157, v156
	v_mov_b32_e32 v174, v156
	v_mov_b32_e32 v175, v156
	v_mov_b32_e32 v160, v156
	v_mov_b32_e32 v161, v156
	v_mov_b32_e32 v188, v156
	v_mov_b32_e32 v189, v156
	v_mov_b32_e32 v158, v156
	v_mov_b32_e32 v159, v156
	v_mov_b32_e32 v172, v156
	v_mov_b32_e32 v173, v156
	v_mov_b32_e32 v164, v156
	v_mov_b32_e32 v165, v156
	v_mov_b32_e32 v192, v156
	v_mov_b32_e32 v193, v156
	v_mov_b32_e32 v162, v156
	v_mov_b32_e32 v163, v156
	v_mov_b32_e32 v190, v156
	v_mov_b32_e32 v191, v156
	v_mov_b32_e32 v168, v156
	v_mov_b32_e32 v169, v156
	v_mov_b32_e32 v194, v156
	v_mov_b32_e32 v195, v156
	v_mov_b32_e32 v166, v156
	v_mov_b32_e32 v167, v156
	v_mov_b32_e32 v186, v156
	v_mov_b32_e32 v187, v156
	v_mov_b32_e32 v170, v156
	v_mov_b32_e32 v171, v156
	v_mov_b32_e32 v196, v156
	v_mov_b32_e32 v197, v156
; __device__ void phase_peer(const Params& p, int l, float* xout, char* smem) {
;     ...
;         __builtin_amdgcn_s_setprio(3); PEER_LOAD(uB, vB, suB, svB, gB, e0 + PB); __builtin_amdgcn_s_setprio(2);
;         PEER_COMPUTE(uA, vA, suA, svA, gA);
.LBB0_1261:
	s_add_i32 s28, s66, 4
	s_setprio 3
	ds_read2st64_b64 v[0:3], v202 offset1:1
	s_waitcnt lgkmcnt(0)
	v_readfirstlane_b32 s4, v0
	s_mul_i32 s41, s4, 0xa80
	s_mul_hi_i32 s5, s4, 0xa80
	s_add_u32 s68, s42, s41
	s_mul_hi_i32 s67, s4, 0xa80
	s_mulk_i32 s4, 0xa80
	s_addc_u32 s69, s43, s5
	s_add_u32 s72, s90, s4
	v_readfirstlane_b32 s4, v1
	s_addc_u32 s73, s91, s67
	s_mul_i32 s41, s4, 0xa80
	global_load_dwordx4 v[64:67], v73, s[68:69]
	v_lshl_add_u64 v[4:5], s[68:69], 0, v[74:75]
	s_mul_hi_i32 s5, s4, 0xa80
	s_add_u32 s68, s42, s41
	s_addc_u32 s69, s43, s5
	s_mul_hi_i32 s5, s4, 0xa80
	s_mulk_i32 s4, 0xa80
	global_load_ubyte v231, v[4:5], off offset:1024
	global_load_dwordx2 v[50:51], v176, s[72:73]
	global_load_dwordx2 v[52:53], v176, s[72:73] offset:512
	global_load_dwordx2 v[54:55], v176, s[72:73] offset:1024
	v_lshl_add_u64 v[4:5], s[72:73], 0, v[74:75]
	s_add_u32 s72, s90, s4
	v_lshl_add_u64 v[0:1], s[68:69], 0, v[74:75]
	global_load_ubyte v238, v[4:5], off offset:1536
	s_addc_u32 s73, s91, s5
	global_load_dwordx4 v[68:71], v73, s[68:69]
	global_load_ubyte v239, v[0:1], off offset:1024
	global_load_dwordx2 v[44:45], v176, s[72:73]
	global_load_dwordx2 v[46:47], v176, s[72:73] offset:512
	global_load_dwordx2 v[48:49], v176, s[72:73] offset:1024
	v_lshl_add_u64 v[0:1], s[72:73], 0, v[74:75]
	global_load_ubyte v208, v[0:1], off offset:1536
	v_readfirstlane_b32 s67, v2
	v_readfirstlane_b32 s41, v3
	s_setprio 2
	s_waitcnt vmcnt(22)
	v_lshlrev_b32_sdwa v6, v230, v205 dst_sel:DWORD dst_unused:UNUSED_PAD src0_sel:DWORD src1_sel:BYTE_0
	v_cvt_scalef32_pk_f32_fp4 v[0:1], v56, v6
	v_pk_fma_f32 v[0:1], v[0:1], v[102:103], 0 op_sel_hi:[1,1,0]
	v_cvt_scalef32_pk_f32_fp4 v[2:3], v56, v6 op_sel:[1,0,0]
	v_cvt_scalef32_pk_f32_fp4 v[4:5], v56, v6 op_sel:[0,1,0]
	v_pk_fma_f32 v[2:3], v[2:3], v[104:105], 0 op_sel_hi:[1,1,0]
	v_pk_fma_f32 v[0:1], v[4:5], v[106:107], v[0:1]
	v_cvt_scalef32_pk_f32_fp4 v[4:5], v56, v6 op_sel:[1,1,0]
	v_pk_fma_f32 v[2:3], v[4:5], v[110:111], v[2:3]
	v_cvt_scalef32_pk_f32_fp4 v[4:5], v57, v6
	v_pk_fma_f32 v[0:1], v[4:5], v[128:129], v[0:1]
	v_cvt_scalef32_pk_f32_fp4 v[4:5], v57, v6 op_sel:[1,0,0]
	v_pk_fma_f32 v[2:3], v[4:5], v[134:135], v[2:3]
	v_cvt_scalef32_pk_f32_fp4 v[4:5], v57, v6 op_sel:[0,1,0]
	v_pk_fma_f32 v[0:1], v[4:5], v[136:137], v[0:1]
	v_cvt_scalef32_pk_f32_fp4 v[4:5], v57, v6 op_sel:[1,1,0]
	v_pk_fma_f32 v[2:3], v[4:5], v[138:139], v[2:3]
	v_cvt_scalef32_pk_f32_fp4 v[4:5], v58, v6
	v_pk_fma_f32 v[0:1], v[4:5], v[140:141], v[0:1]
	v_cvt_scalef32_pk_f32_fp4 v[4:5], v58, v6 op_sel:[1,0,0]
	v_pk_fma_f32 v[2:3], v[4:5], v[142:143], v[2:3]
	v_cvt_scalef32_pk_f32_fp4 v[4:5], v58, v6 op_sel:[0,1,0]
	v_pk_fma_f32 v[0:1], v[4:5], v[144:145], v[0:1]
	v_cvt_scalef32_pk_f32_fp4 v[4:5], v58, v6 op_sel:[1,1,0]
	v_pk_fma_f32 v[2:3], v[4:5], v[146:147], v[2:3]
	v_cvt_scalef32_pk_f32_fp4 v[4:5], v59, v6
	v_pk_fma_f32 v[0:1], v[4:5], v[148:149], v[0:1]
	v_cvt_scalef32_pk_f32_fp4 v[4:5], v59, v6 op_sel:[1,0,0]
	v_pk_fma_f32 v[2:3], v[4:5], v[150:151], v[2:3]
	v_cvt_scalef32_pk_f32_fp4 v[4:5], v59, v6 op_sel:[0,1,0]
	v_pk_fma_f32 v[0:1], v[4:5], v[152:153], v[0:1]
	v_cvt_scalef32_pk_f32_fp4 v[4:5], v59, v6 op_sel:[1,1,0]
	v_pk_fma_f32 v[2:3], v[4:5], v[154:155], v[2:3]
	s_waitcnt vmcnt(16)
	v_lshlrev_b32_sdwa v7, v230, v206 dst_sel:DWORD dst_unused:UNUSED_PAD src0_sel:DWORD src1_sel:BYTE_0
	v_pk_add_f32 v[0:1], v[0:1], v[2:3]
	v_cvt_scalef32_pk_f32_fp4 v[2:3], v60, v7 op_sel:[1,0,0]
	v_add_f32_e32 v6, v0, v1
	v_cvt_scalef32_pk_f32_fp4 v[0:1], v60, v7
	v_pk_fma_f32 v[0:1], v[0:1], v[102:103], 0 op_sel_hi:[1,1,0]
	v_cvt_scalef32_pk_f32_fp4 v[4:5], v60, v7 op_sel:[0,1,0]
	v_pk_fma_f32 v[2:3], v[2:3], v[104:105], 0 op_sel_hi:[1,1,0]
	v_pk_fma_f32 v[0:1], v[4:5], v[106:107], v[0:1]
	v_cvt_scalef32_pk_f32_fp4 v[4:5], v60, v7 op_sel:[1,1,0]
	v_pk_fma_f32 v[2:3], v[4:5], v[110:111], v[2:3]
	v_cvt_scalef32_pk_f32_fp4 v[4:5], v61, v7
	v_pk_fma_f32 v[0:1], v[4:5], v[128:129], v[0:1]
	v_cvt_scalef32_pk_f32_fp4 v[4:5], v61, v7 op_sel:[1,0,0]
	v_pk_fma_f32 v[2:3], v[4:5], v[134:135], v[2:3]
	v_cvt_scalef32_pk_f32_fp4 v[4:5], v61, v7 op_sel:[0,1,0]
	v_pk_fma_f32 v[0:1], v[4:5], v[136:137], v[0:1]
	v_cvt_scalef32_pk_f32_fp4 v[4:5], v61, v7 op_sel:[1,1,0]
	v_pk_fma_f32 v[2:3], v[4:5], v[138:139], v[2:3]
	v_cvt_scalef32_pk_f32_fp4 v[4:5], v62, v7
	v_pk_fma_f32 v[0:1], v[4:5], v[140:141], v[0:1]
	v_cvt_scalef32_pk_f32_fp4 v[4:5], v62, v7 op_sel:[1,0,0]
	v_pk_fma_f32 v[2:3], v[4:5], v[142:143], v[2:3]
	v_cvt_scalef32_pk_f32_fp4 v[4:5], v62, v7 op_sel:[0,1,0]
	v_pk_fma_f32 v[0:1], v[4:5], v[144:145], v[0:1]
	v_cvt_scalef32_pk_f32_fp4 v[4:5], v62, v7 op_sel:[1,1,0]
	v_pk_fma_f32 v[2:3], v[4:5], v[146:147], v[2:3]
	v_cvt_scalef32_pk_f32_fp4 v[4:5], v63, v7
	v_pk_fma_f32 v[0:1], v[4:5], v[148:149], v[0:1]
	v_cvt_scalef32_pk_f32_fp4 v[4:5], v63, v7 op_sel:[1,0,0]
	v_pk_fma_f32 v[2:3], v[4:5], v[150:151], v[2:3]
	v_cvt_scalef32_pk_f32_fp4 v[4:5], v63, v7 op_sel:[0,1,0]
	v_pk_fma_f32 v[0:1], v[4:5], v[152:153], v[0:1]
	v_cvt_scalef32_pk_f32_fp4 v[4:5], v63, v7 op_sel:[1,1,0]
	v_pk_fma_f32 v[2:3], v[4:5], v[154:155], v[2:3]
	v_lshlrev_b32_sdwa v57, v230, v203 dst_sel:DWORD dst_unused:UNUSED_PAD src0_sel:DWORD src1_sel:BYTE_0
	v_pk_add_f32 v[0:1], v[0:1], v[2:3]
	s_nop 0
	v_add_f32_e32 v0, v0, v1
	v_add_f32_dpp v1, v6, v6 quad_perm:[1,0,3,2] row_mask:0xf bank_mask:0xf bound_ctrl:1
	s_nop 0
	v_add_f32_dpp v0, v0, v0 quad_perm:[1,0,3,2] row_mask:0xf bank_mask:0xf bound_ctrl:1
	v_add_f32_dpp v1, v1, v1 quad_perm:[2,3,0,1] row_mask:0xf bank_mask:0xf bound_ctrl:1
	s_nop 0
	v_add_f32_dpp v0, v0, v0 quad_perm:[2,3,0,1] row_mask:0xf bank_mask:0xf bound_ctrl:1
; __device__ void phase_peer(const Params& p, int l, float* xout, char* smem) {
;     ...
;     {
;       u32x4 uA[PB], uB[PB]; u32x2 vA[PB][3], vB[PB][3];
;       unsigned char suA[PB], suB[PB], svA[PB], svB[PB];
;       float gA[PB], gB[PB];
;       PEER_LOAD(uA, vA, suA, svA, gA, 0);
; #pragma unroll 1
;       for (int e0 = 0; e0 < 128; e0 += 2 * PB) {
;         __builtin_amdgcn_s_setprio(3); PEER_LOAD(uB, vB, suB, svB, gB, e0 + PB); __builtin_amdgcn_s_setprio(2);
;         PEER_COMPUTE(uA, vA, suA, svA, gA);
;         __builtin_amdgcn_s_setprio(3); PEER_LOAD(uA, vA, suA, svA, gA, e0 + 2 * PB); __builtin_amdgcn_s_setprio(2);
	v_add_f32_dpp v1, v1, v1 row_half_mirror row_mask:0xf bank_mask:0xf bound_ctrl:1
	s_nop 0
	v_add_f32_dpp v0, v0, v0 row_half_mirror row_mask:0xf bank_mask:0xf bound_ctrl:1
	v_add_f32_dpp v1, v1, v1 row_mirror row_mask:0xf bank_mask:0xf bound_ctrl:1
	s_nop 0
	v_add_f32_dpp v0, v0, v0 row_mirror row_mask:0xf bank_mask:0xf bound_ctrl:1
	v_add_f32_dpp v1, v1, v1 row_bcast:15 row_mask:0xf bank_mask:0xf bound_ctrl:1
	s_nop 0
	v_add_f32_dpp v0, v0, v0 row_bcast:15 row_mask:0xf bank_mask:0xf bound_ctrl:1
	v_add_f32_dpp v1, v1, v1 row_bcast:31 row_mask:0xf bank_mask:0xf bound_ctrl:1
	s_nop 0
	v_readlane_b32 s4, v1, 63
	v_add_f32_dpp v0, v0, v0 row_bcast:31 row_mask:0xf bank_mask:0xf bound_ctrl:1
	s_nop 0
	v_mul_f32_e64 v1, s4, s4
	v_fmamk_f32 v1, v1, 0x3dd2d3e7, v213
	v_mul_f32_e32 v1, s4, v1
	v_exp_f32_e32 v1, v1
	v_readlane_b32 s5, v0, 63
	v_add_f32_e32 v1, 1.0, v1
	v_rcp_f32_e32 v1, v1
	s_nop 0
	v_fma_f32 v0, -s4, v1, s4
	v_mul_f32_e32 v56, s40, v0
	v_cvt_scalef32_pk32_f32_fp6 v[0:31], v[32:37], v57
	v_pk_fma_f32 v[32:33], v[56:57], v[0:1], v[196:197] op_sel_hi:[0,1,1]
	v_mul_f32_e64 v0, s5, s5
	v_fmamk_f32 v0, v0, 0x3dd2d3e7, v213
	v_mul_f32_e32 v0, s5, v0
	v_exp_f32_e32 v0, v0
	v_pk_fma_f32 v[34:35], v[56:57], v[2:3], v[170:171] op_sel_hi:[0,1,1]
	v_pk_fma_f32 v[36:37], v[56:57], v[4:5], v[186:187] op_sel_hi:[0,1,1]
	v_pk_fma_f32 v[58:59], v[56:57], v[6:7], v[166:167] op_sel_hi:[0,1,1]
	v_add_f32_e32 v0, 1.0, v0
	v_rcp_f32_e32 v0, v0
	v_pk_fma_f32 v[60:61], v[56:57], v[8:9], v[194:195] op_sel_hi:[0,1,1]
	v_pk_fma_f32 v[62:63], v[56:57], v[10:11], v[168:169] op_sel_hi:[0,1,1]
	v_pk_fma_f32 v[166:167], v[56:57], v[12:13], v[190:191] op_sel_hi:[0,1,1]
	v_pk_fma_f32 v[162:163], v[56:57], v[14:15], v[162:163] op_sel_hi:[0,1,1]
	v_pk_fma_f32 v[194:195], v[56:57], v[16:17], v[192:193] op_sel_hi:[0,1,1]
	v_pk_fma_f32 v[164:165], v[56:57], v[18:19], v[164:165] op_sel_hi:[0,1,1]
	v_pk_fma_f32 v[210:211], v[56:57], v[20:21], v[172:173] op_sel_hi:[0,1,1]
	v_pk_fma_f32 v[158:159], v[56:57], v[22:23], v[158:159] op_sel_hi:[0,1,1]
	v_pk_fma_f32 v[232:233], v[56:57], v[24:25], v[188:189] op_sel_hi:[0,1,1]
	v_pk_fma_f32 v[234:235], v[56:57], v[26:27], v[160:161] op_sel_hi:[0,1,1]
	v_pk_fma_f32 v[236:237], v[56:57], v[28:29], v[174:175] op_sel_hi:[0,1,1]
	v_pk_fma_f32 v[56:57], v[56:57], v[30:31], v[156:157] op_sel_hi:[0,1,1]
	v_fma_f32 v0, -s5, v0, s5
	s_waitcnt vmcnt(12)
	v_lshlrev_b32_sdwa v156, v230, v204 dst_sel:DWORD dst_unused:UNUSED_PAD src0_sel:DWORD src1_sel:BYTE_0
	v_mul_f32_e32 v206, s11, v0
	v_cvt_scalef32_pk32_f32_fp6 v[0:31], v[38:43], v156
	v_pk_fma_f32 v[168:169], v[206:207], v[0:1], v[32:33] op_sel_hi:[0,1,1]
	v_pk_fma_f32 v[170:171], v[206:207], v[2:3], v[34:35] op_sel_hi:[0,1,1]
	v_pk_fma_f32 v[172:173], v[206:207], v[4:5], v[36:37] op_sel_hi:[0,1,1]
	v_pk_fma_f32 v[174:175], v[206:207], v[6:7], v[58:59] op_sel_hi:[0,1,1]
	v_pk_fma_f32 v[186:187], v[206:207], v[8:9], v[60:61] op_sel_hi:[0,1,1]
	v_pk_fma_f32 v[188:189], v[206:207], v[10:11], v[62:63] op_sel_hi:[0,1,1]
	v_pk_fma_f32 v[190:191], v[206:207], v[12:13], v[166:167] op_sel_hi:[0,1,1]
	v_pk_fma_f32 v[192:193], v[206:207], v[14:15], v[162:163] op_sel_hi:[0,1,1]
	v_pk_fma_f32 v[194:195], v[206:207], v[16:17], v[194:195] op_sel_hi:[0,1,1]
	v_pk_fma_f32 v[196:197], v[206:207], v[18:19], v[164:165] op_sel_hi:[0,1,1]
	v_pk_fma_f32 v[156:157], v[206:207], v[20:21], v[210:211] op_sel_hi:[0,1,1]
	v_pk_fma_f32 v[158:159], v[206:207], v[22:23], v[158:159] op_sel_hi:[0,1,1]
	v_pk_fma_f32 v[160:161], v[206:207], v[24:25], v[232:233] op_sel_hi:[0,1,1]
	v_pk_fma_f32 v[162:163], v[206:207], v[26:27], v[234:235] op_sel_hi:[0,1,1]
	v_pk_fma_f32 v[164:165], v[206:207], v[28:29], v[236:237] op_sel_hi:[0,1,1]
	v_pk_fma_f32 v[166:167], v[206:207], v[30:31], v[56:57] op_sel_hi:[0,1,1]
	s_setprio 3
	s_add_i32 s4, s66, 8
	s_min_u32 s4, s4, 0x7f
	v_lshl_add_u32 v0, s4, 2, v79
	ds_read2st64_b32 v[0:1], v0 offset1:2
	s_waitcnt lgkmcnt(0)
	v_readfirstlane_b32 s4, v0
	s_mul_i32 s11, s4, 0xa80
	s_mul_hi_i32 s5, s4, 0xa80
	s_add_u32 s68, s42, s11
	s_mul_hi_i32 s40, s4, 0xa80
	s_mulk_i32 s4, 0xa80
	s_addc_u32 s69, s43, s5
	s_add_u32 s72, s90, s4
	s_addc_u32 s73, s91, s40
	s_min_u32 s4, s28, 0x7a
	v_lshl_add_u64 v[2:3], s[68:69], 0, v[74:75]
	v_lshl_add_u32 v0, s4, 2, v79
	global_load_dwordx4 v[56:59], v73, s[68:69]
	global_load_ubyte v205, v[2:3], off offset:1024
	global_load_dwordx2 v[32:33], v176, s[72:73]
	ds_read2_b32 v[2:3], v0 offset0:5 offset1:133
	v_lshl_add_u64 v[4:5], s[72:73], 0, v[74:75]
	global_load_dwordx2 v[34:35], v176, s[72:73] offset:512
	global_load_dwordx2 v[36:37], v176, s[72:73] offset:1024
	global_load_ubyte v203, v[4:5], off offset:1536
	v_readfirstlane_b32 s40, v1
	s_waitcnt lgkmcnt(0)
	v_readfirstlane_b32 s4, v2
	s_mul_i32 s11, s4, 0xa80
	s_mul_hi_i32 s5, s4, 0xa80
	s_add_u32 s68, s42, s11
	s_addc_u32 s69, s43, s5
	s_mul_hi_i32 s5, s4, 0xa80
	s_mulk_i32 s4, 0xa80
	s_add_u32 s72, s90, s4
	v_lshl_add_u64 v[4:5], s[68:69], 0, v[74:75]
	s_addc_u32 s73, s91, s5
	global_load_dwordx4 v[60:63], v73, s[68:69]
	global_load_ubyte v206, v[4:5], off offset:1024
	global_load_dwordx2 v[38:39], v176, s[72:73]
	global_load_dwordx2 v[40:41], v176, s[72:73] offset:512
	global_load_dwordx2 v[42:43], v176, s[72:73] offset:1024
	v_lshl_add_u64 v[4:5], s[72:73], 0, v[74:75]
	global_load_ubyte v204, v[4:5], off offset:1536
	v_readfirstlane_b32 s11, v3
	s_setprio 2
	s_waitcnt vmcnt(22)
	v_lshlrev_b32_e32 v6, 23, v231
	v_cvt_scalef32_pk_f32_fp4 v[0:1], v64, v6
	v_pk_fma_f32 v[0:1], v[0:1], v[102:103], 0 op_sel_hi:[1,1,0]
	v_cvt_scalef32_pk_f32_fp4 v[2:3], v64, v6 op_sel:[1,0,0]
	v_cvt_scalef32_pk_f32_fp4 v[4:5], v64, v6 op_sel:[0,1,0]
	v_pk_fma_f32 v[2:3], v[2:3], v[104:105], 0 op_sel_hi:[1,1,0]
	v_pk_fma_f32 v[0:1], v[4:5], v[106:107], v[0:1]
	v_cvt_scalef32_pk_f32_fp4 v[4:5], v64, v6 op_sel:[1,1,0]
	v_pk_fma_f32 v[2:3], v[4:5], v[110:111], v[2:3]
	v_cvt_scalef32_pk_f32_fp4 v[4:5], v65, v6
	v_pk_fma_f32 v[0:1], v[4:5], v[128:129], v[0:1]
	v_cvt_scalef32_pk_f32_fp4 v[4:5], v65, v6 op_sel:[1,0,0]
	v_pk_fma_f32 v[2:3], v[4:5], v[134:135], v[2:3]
	v_cvt_scalef32_pk_f32_fp4 v[4:5], v65, v6 op_sel:[0,1,0]
	v_pk_fma_f32 v[0:1], v[4:5], v[136:137], v[0:1]
	v_cvt_scalef32_pk_f32_fp4 v[4:5], v65, v6 op_sel:[1,1,0]
	v_pk_fma_f32 v[2:3], v[4:5], v[138:139], v[2:3]
	v_cvt_scalef32_pk_f32_fp4 v[4:5], v66, v6
	v_pk_fma_f32 v[0:1], v[4:5], v[140:141], v[0:1]
	v_cvt_scalef32_pk_f32_fp4 v[4:5], v66, v6 op_sel:[1,0,0]
	v_pk_fma_f32 v[2:3], v[4:5], v[142:143], v[2:3]
	v_cvt_scalef32_pk_f32_fp4 v[4:5], v66, v6 op_sel:[0,1,0]
	v_pk_fma_f32 v[0:1], v[4:5], v[144:145], v[0:1]
	v_cvt_scalef32_pk_f32_fp4 v[4:5], v66, v6 op_sel:[1,1,0]
	v_pk_fma_f32 v[2:3], v[4:5], v[146:147], v[2:3]
	v_cvt_scalef32_pk_f32_fp4 v[4:5], v67, v6
	v_pk_fma_f32 v[0:1], v[4:5], v[148:149], v[0:1]
	v_cvt_scalef32_pk_f32_fp4 v[4:5], v67, v6 op_sel:[1,0,0]
	v_pk_fma_f32 v[2:3], v[4:5], v[150:151], v[2:3]
	v_cvt_scalef32_pk_f32_fp4 v[4:5], v67, v6 op_sel:[0,1,0]
	v_pk_fma_f32 v[0:1], v[4:5], v[152:153], v[0:1]
	v_cvt_scalef32_pk_f32_fp4 v[4:5], v67, v6 op_sel:[1,1,0]
	v_pk_fma_f32 v[2:3], v[4:5], v[154:155], v[2:3]
	s_waitcnt vmcnt(16)
	v_lshlrev_b32_e32 v7, 23, v239
	v_pk_add_f32 v[0:1], v[0:1], v[2:3]
	v_cvt_scalef32_pk_f32_fp4 v[2:3], v68, v7 op_sel:[1,0,0]
	v_add_f32_e32 v6, v0, v1
	v_cvt_scalef32_pk_f32_fp4 v[0:1], v68, v7
	v_pk_fma_f32 v[0:1], v[0:1], v[102:103], 0 op_sel_hi:[1,1,0]
	v_cvt_scalef32_pk_f32_fp4 v[4:5], v68, v7 op_sel:[0,1,0]
	v_pk_fma_f32 v[2:3], v[2:3], v[104:105], 0 op_sel_hi:[1,1,0]
	v_pk_fma_f32 v[0:1], v[4:5], v[106:107], v[0:1]
	v_cvt_scalef32_pk_f32_fp4 v[4:5], v68, v7 op_sel:[1,1,0]
	v_pk_fma_f32 v[2:3], v[4:5], v[110:111], v[2:3]
	v_cvt_scalef32_pk_f32_fp4 v[4:5], v69, v7
	v_pk_fma_f32 v[0:1], v[4:5], v[128:129], v[0:1]
	v_cvt_scalef32_pk_f32_fp4 v[4:5], v69, v7 op_sel:[1,0,0]
	v_pk_fma_f32 v[2:3], v[4:5], v[134:135], v[2:3]
	v_cvt_scalef32_pk_f32_fp4 v[4:5], v69, v7 op_sel:[0,1,0]
	v_pk_fma_f32 v[0:1], v[4:5], v[136:137], v[0:1]
	v_cvt_scalef32_pk_f32_fp4 v[4:5], v69, v7 op_sel:[1,1,0]
	v_pk_fma_f32 v[2:3], v[4:5], v[138:139], v[2:3]
	v_cvt_scalef32_pk_f32_fp4 v[4:5], v70, v7
	v_pk_fma_f32 v[0:1], v[4:5], v[140:141], v[0:1]
	v_cvt_scalef32_pk_f32_fp4 v[4:5], v70, v7 op_sel:[1,0,0]
	v_pk_fma_f32 v[2:3], v[4:5], v[142:143], v[2:3]
	v_cvt_scalef32_pk_f32_fp4 v[4:5], v70, v7 op_sel:[0,1,0]
	v_pk_fma_f32 v[0:1], v[4:5], v[144:145], v[0:1]
	v_cvt_scalef32_pk_f32_fp4 v[4:5], v70, v7 op_sel:[1,1,0]
	v_pk_fma_f32 v[2:3], v[4:5], v[146:147], v[2:3]
	v_cvt_scalef32_pk_f32_fp4 v[4:5], v71, v7
	v_pk_fma_f32 v[0:1], v[4:5], v[148:149], v[0:1]
	v_cvt_scalef32_pk_f32_fp4 v[4:5], v71, v7 op_sel:[1,0,0]
	v_pk_fma_f32 v[2:3], v[4:5], v[150:151], v[2:3]
	v_cvt_scalef32_pk_f32_fp4 v[4:5], v71, v7 op_sel:[0,1,0]
	v_pk_fma_f32 v[0:1], v[4:5], v[152:153], v[0:1]
	v_cvt_scalef32_pk_f32_fp4 v[4:5], v71, v7 op_sel:[1,1,0]
	v_pk_fma_f32 v[2:3], v[4:5], v[154:155], v[2:3]
	v_lshlrev_b32_e32 v65, 23, v238
	v_pk_add_f32 v[0:1], v[0:1], v[2:3]
	v_add_u32_e32 v202, 16, v202
	v_add_f32_e32 v0, v0, v1
	v_add_f32_dpp v1, v6, v6 quad_perm:[1,0,3,2] row_mask:0xf bank_mask:0xf bound_ctrl:1
	s_cmpk_gt_u32 s28, 0x7b
	v_add_f32_dpp v0, v0, v0 quad_perm:[1,0,3,2] row_mask:0xf bank_mask:0xf bound_ctrl:1
	v_add_f32_dpp v1, v1, v1 quad_perm:[2,3,0,1] row_mask:0xf bank_mask:0xf bound_ctrl:1
	s_mov_b32 s66, s28
	v_add_f32_dpp v0, v0, v0 quad_perm:[2,3,0,1] row_mask:0xf bank_mask:0xf bound_ctrl:1
	v_add_f32_dpp v1, v1, v1 row_half_mirror row_mask:0xf bank_mask:0xf bound_ctrl:1
	s_nop 0
	v_add_f32_dpp v0, v0, v0 row_half_mirror row_mask:0xf bank_mask:0xf bound_ctrl:1
	v_add_f32_dpp v1, v1, v1 row_mirror row_mask:0xf bank_mask:0xf bound_ctrl:1
	s_nop 0
	v_add_f32_dpp v0, v0, v0 row_mirror row_mask:0xf bank_mask:0xf bound_ctrl:1
	v_add_f32_dpp v1, v1, v1 row_bcast:15 row_mask:0xf bank_mask:0xf bound_ctrl:1
	s_nop 0
	v_add_f32_dpp v0, v0, v0 row_bcast:15 row_mask:0xf bank_mask:0xf bound_ctrl:1
	v_add_f32_dpp v1, v1, v1 row_bcast:31 row_mask:0xf bank_mask:0xf bound_ctrl:1
	s_nop 0
	v_readlane_b32 s4, v1, 63
	v_add_f32_dpp v0, v0, v0 row_bcast:31 row_mask:0xf bank_mask:0xf bound_ctrl:1
	s_nop 0
	v_mul_f32_e64 v1, s4, s4
	v_fmamk_f32 v1, v1, 0x3dd2d3e7, v213
	v_mul_f32_e32 v1, s4, v1
	v_exp_f32_e32 v1, v1
	v_readlane_b32 s5, v0, 63
	v_add_f32_e32 v1, 1.0, v1
	v_rcp_f32_e32 v1, v1
	s_nop 0
	v_fma_f32 v0, -s4, v1, s4
	v_mul_f32_e32 v64, s67, v0
	v_cvt_scalef32_pk32_f32_fp6 v[0:31], v[50:55], v65
	v_pk_fma_f32 v[50:51], v[64:65], v[0:1], v[168:169] op_sel_hi:[0,1,1]
	v_mul_f32_e64 v0, s5, s5
	v_fmamk_f32 v0, v0, 0x3dd2d3e7, v213
	v_mul_f32_e32 v0, s5, v0
	v_exp_f32_e32 v0, v0
	v_pk_fma_f32 v[232:233], v[64:65], v[26:27], v[162:163] op_sel_hi:[0,1,1]
	s_waitcnt vmcnt(12)
; __device__ void phase_peer(const Params& p, int l, float* xout, char* smem) {
;     ...
;     {
;       u32x4 uA[PB], uB[PB]; u32x2 vA[PB][3], vB[PB][3];
;       unsigned char suA[PB], suB[PB], svA[PB], svB[PB];
;       float gA[PB], gB[PB];
;       PEER_LOAD(uA, vA, suA, svA, gA, 0);
; #pragma unroll 1
;       for (int e0 = 0; e0 < 128; e0 += 2 * PB) {
;         __builtin_amdgcn_s_setprio(3); PEER_LOAD(uB, vB, suB, svB, gB, e0 + PB); __builtin_amdgcn_s_setprio(2);
;         PEER_COMPUTE(uA, vA, suA, svA, gA);
;         __builtin_amdgcn_s_setprio(3); PEER_LOAD(uA, vA, suA, svA, gA, e0 + 2 * PB); __builtin_amdgcn_s_setprio(2);
;         PEER_COMPUTE(uB, vB, suB, svB, gB);
;       }
;       __builtin_amdgcn_s_setprio(0);
;     }
;     ...
;     float y[32];
;     float sum = 0.f;
; #pragma unroll
;     for (int i = 0; i < 8; ++i) {
;       y[i * 4] = ALPHA * xf2[i * 2][0] + acc2[i * 2][0]; y[i * 4 + 1] = ALPHA * xf2[i * 2][1] + acc2[i * 2][1];
;       y[i * 4 + 2] = ALPHA * xf2[i * 2 + 1][0] + acc2[i * 2 + 1][0]; y[i * 4 + 3] = ALPHA * xf2[i * 2 + 1][1] + acc2[i * 2 + 1][1];
;       sum += (y[i * 4] + y[i * 4 + 1]) + (y[i * 4 + 2] + y[i * 4 + 3]);
;     }
	v_lshlrev_b32_e32 v162, 23, v208
	v_pk_fma_f32 v[52:53], v[64:65], v[2:3], v[170:171] op_sel_hi:[0,1,1]
	v_add_f32_e32 v0, 1.0, v0
	v_rcp_f32_e32 v0, v0
	v_pk_fma_f32 v[54:55], v[64:65], v[4:5], v[172:173] op_sel_hi:[0,1,1]
	v_pk_fma_f32 v[66:67], v[64:65], v[6:7], v[174:175] op_sel_hi:[0,1,1]
	v_pk_fma_f32 v[68:69], v[64:65], v[8:9], v[186:187] op_sel_hi:[0,1,1]
	v_fma_f32 v0, -s5, v0, s5
	v_pk_fma_f32 v[70:71], v[64:65], v[10:11], v[188:189] op_sel_hi:[0,1,1]
	v_pk_fma_f32 v[172:173], v[64:65], v[12:13], v[190:191] op_sel_hi:[0,1,1]
	v_pk_fma_f32 v[174:175], v[64:65], v[14:15], v[192:193] op_sel_hi:[0,1,1]
	v_pk_fma_f32 v[188:189], v[64:65], v[16:17], v[194:195] op_sel_hi:[0,1,1]
	v_pk_fma_f32 v[210:211], v[64:65], v[18:19], v[196:197] op_sel_hi:[0,1,1]
	v_pk_fma_f32 v[156:157], v[64:65], v[20:21], v[156:157] op_sel_hi:[0,1,1]
	v_pk_fma_f32 v[158:159], v[64:65], v[22:23], v[158:159] op_sel_hi:[0,1,1]
	v_pk_fma_f32 v[160:161], v[64:65], v[24:25], v[160:161] op_sel_hi:[0,1,1]
	v_pk_fma_f32 v[234:235], v[64:65], v[28:29], v[164:165] op_sel_hi:[0,1,1]
	v_pk_fma_f32 v[64:65], v[64:65], v[30:31], v[166:167] op_sel_hi:[0,1,1]
	v_mul_f32_e32 v236, s41, v0
	v_cvt_scalef32_pk32_f32_fp6 v[0:31], v[44:49], v162
	v_pk_fma_f32 v[196:197], v[236:237], v[0:1], v[50:51] op_sel_hi:[0,1,1]
	v_pk_fma_f32 v[170:171], v[236:237], v[2:3], v[52:53] op_sel_hi:[0,1,1]
	v_pk_fma_f32 v[186:187], v[236:237], v[4:5], v[54:55] op_sel_hi:[0,1,1]
	v_pk_fma_f32 v[166:167], v[236:237], v[6:7], v[66:67] op_sel_hi:[0,1,1]
	v_pk_fma_f32 v[194:195], v[236:237], v[8:9], v[68:69] op_sel_hi:[0,1,1]
	v_pk_fma_f32 v[168:169], v[236:237], v[10:11], v[70:71] op_sel_hi:[0,1,1]
	v_pk_fma_f32 v[190:191], v[236:237], v[12:13], v[172:173] op_sel_hi:[0,1,1]
	v_pk_fma_f32 v[162:163], v[236:237], v[14:15], v[174:175] op_sel_hi:[0,1,1]
	v_pk_fma_f32 v[192:193], v[236:237], v[16:17], v[188:189] op_sel_hi:[0,1,1]
	v_pk_fma_f32 v[164:165], v[236:237], v[18:19], v[210:211] op_sel_hi:[0,1,1]
	v_pk_fma_f32 v[172:173], v[236:237], v[20:21], v[156:157] op_sel_hi:[0,1,1]
	v_pk_fma_f32 v[158:159], v[236:237], v[22:23], v[158:159] op_sel_hi:[0,1,1]
	v_pk_fma_f32 v[188:189], v[236:237], v[24:25], v[160:161] op_sel_hi:[0,1,1]
	v_pk_fma_f32 v[160:161], v[236:237], v[26:27], v[232:233] op_sel_hi:[0,1,1]
	v_pk_fma_f32 v[174:175], v[236:237], v[28:29], v[234:235] op_sel_hi:[0,1,1]
	v_pk_fma_f32 v[156:157], v[236:237], v[30:31], v[64:65] op_sel_hi:[0,1,1]
	s_cbranch_scc0 .LBB0_1261
	s_setprio 0
	global_load_dwordx4 v[28:31], v[80:81], off
	global_load_dwordx4 v[38:41], v[80:81], off offset:16
	global_load_dwordx4 v[42:45], v[82:83], off offset:16
	global_load_dwordx4 v[32:35], v[82:83], off
	s_mov_b64 s[98:99], exec
	s_mov_b64 exec, 1
	v_mov_b32_e32 v254, 1
	global_atomic_add v253, v177, v254, s[92:93] sc0
	s_mov_b64 exec, s[98:99]
	v_mov_b32_e32 v14, v196
	v_mov_b32_e32 v15, v170
	v_mov_b32_e32 v170, v197
	v_mov_b32_e32 v16, v186
	v_mov_b32_e32 v17, v166
	v_mov_b32_e32 v166, v187
	v_pk_fma_f32 v[14:15], v[92:93], s[10:11], v[14:15] op_sel_hi:[1,0,1]
	v_pk_fma_f32 v[22:23], v[94:95], s[10:11], v[170:171] op_sel_hi:[1,0,1]
	v_pk_fma_f32 v[16:17], v[96:97], s[10:11], v[16:17] op_sel_hi:[1,0,1]
	v_pk_fma_f32 v[24:25], v[98:99], s[10:11], v[166:167] op_sel_hi:[1,0,1]
	v_mov_b32_e32 v10, v194
	v_mov_b32_e32 v11, v168
	v_mov_b32_e32 v168, v195
	s_waitcnt vmcnt(15)
	v_mov_b32_e32 v58, v16
	v_mov_b32_e32 v59, v14
	s_waitcnt vmcnt(9)
	v_mov_b32_e32 v60, v24
	v_mov_b32_e32 v61, v22
	v_mov_b32_e32 v62, v17
	v_mov_b32_e32 v63, v15
	v_mov_b32_e32 v64, v25
	v_mov_b32_e32 v65, v23
	v_mov_b32_e32 v12, v190
	v_mov_b32_e32 v13, v162
	v_mov_b32_e32 v162, v191
	v_pk_fma_f32 v[10:11], v[100:101], s[10:11], v[10:11] op_sel_hi:[1,0,1]
	v_pk_fma_f32 v[18:19], v[108:109], s[10:11], v[168:169] op_sel_hi:[1,0,1]
	v_pk_add_f32 v[58:59], v[58:59], v[60:61]
	v_pk_add_f32 v[60:61], v[62:63], v[64:65]
	v_mov_b32_e32 v6, v192
	v_mov_b32_e32 v7, v164
	v_mov_b32_e32 v164, v193
	v_pk_fma_f32 v[12:13], v[112:113], s[10:11], v[12:13] op_sel_hi:[1,0,1]
	v_pk_fma_f32 v[26:27], v[114:115], s[10:11], v[162:163] op_sel_hi:[1,0,1]
	v_pk_add_f32 v[54:55], v[10:11], v[18:19]
	v_pk_add_f32 v[58:59], v[58:59], v[60:61]
	v_pk_fma_f32 v[6:7], v[116:117], s[10:11], v[6:7] op_sel_hi:[1,0,1]
	v_pk_fma_f32 v[20:21], v[118:119], s[10:11], v[164:165] op_sel_hi:[1,0,1]
	v_pk_add_f32 v[56:57], v[12:13], v[26:27]
	v_pk_add_f32 v[54:55], v[54:55], v[54:55] op_sel_hi:[0,1]
	v_add_f32_e32 v59, 0, v59
	v_mov_b32_e32 v8, v172
	v_mov_b32_e32 v9, v158
	v_mov_b32_e32 v158, v173
	v_mov_b32_e32 v66, v6
	v_mov_b32_e32 v68, v21
	v_mov_b32_e32 v67, v56
	v_mov_b32_e32 v56, v20
	v_mov_b32_e32 v54, v7
	v_add_f32_e32 v69, v58, v59
	v_mov_b32_e32 v2, v188
	v_mov_b32_e32 v3, v160
	v_mov_b32_e32 v160, v189
	v_pk_fma_f32 v[8:9], v[120:121], s[10:11], v[8:9] op_sel_hi:[1,0,1]
	v_pk_fma_f32 v[48:49], v[122:123], s[10:11], v[158:159] op_sel_hi:[1,0,1]
	v_pk_add_f32 v[56:57], v[66:67], v[56:57]
	v_pk_add_f32 v[54:55], v[54:55], v[68:69]
	v_mov_b32_e32 v4, v174
	v_mov_b32_e32 v5, v156
	v_mov_b32_e32 v156, v175
	v_pk_fma_f32 v[2:3], v[124:125], s[10:11], v[2:3] op_sel_hi:[1,0,1]
	v_pk_fma_f32 v[36:37], v[126:127], s[10:11], v[160:161] op_sel_hi:[1,0,1]
	v_pk_add_f32 v[52:53], v[8:9], v[48:49]
	v_pk_add_f32 v[54:55], v[56:57], v[54:55]
	v_pk_fma_f32 v[4:5], v[130:131], s[10:11], v[4:5] op_sel_hi:[1,0,1]
	v_pk_fma_f32 v[46:47], v[132:133], s[10:11], v[156:157] op_sel_hi:[1,0,1]
	v_pk_add_f32 v[50:51], v[2:3], v[36:37]
	v_pk_add_f32 v[52:53], v[52:53], v[52:53] op_sel_hi:[0,1]
	v_pk_add_f32 v[54:55], v[54:55], v[54:55] op_sel_hi:[0,1]
	v_mov_b32_e32 v70, v4
	v_mov_b32_e32 v71, v50
	v_mov_b32_e32 v50, v46
	v_mov_b32_e32 v52, v5
	v_mov_b32_e32 v54, v47
	v_pk_add_f32 v[50:51], v[70:71], v[50:51]
	v_lshl_add_u64 v[0:1], v[90:91], 2, s[20:21]
	v_lshlrev_b32_e32 v176, 2, v76
	s_waitcnt vmcnt(3)
; __device__ void phase_peer(const Params& p, int l, float* xout, char* smem) {
;     ...
;     float mu = wave_sum(sum) * (1.f / D_), q = 0.f;
; #pragma unroll
;     for (int j = 0; j < 32; ++j) { float d = y[j] - mu; q += d * d; }
;     float rstd = rsqrtf(wave_sum(q) * (1.f / D_) + LN_EPS);
; #pragma unroll
;     for (int i = 0; i < 4; ++i) {
;       int c0 = lane * 32 + i * 8;
;       float o[8];
; #pragma unroll
;       for (int j = 0; j < 8; ++j) o[j] = (y[i * 8 + j] - mu) * rstd * g2[c0 + j] + b2[c0 + j];
;       if (xout) {
;         float* op = xout + (long)t * D_ + c0;
;         *(float4*)op = make_float4(o[0], o[1], o[2], o[3]);
;         *(float4*)(op + 4) = make_float4(o[4], o[5], o[6], o[7]);
	v_mov_b32_e32 v56, v28
	v_mov_b32_e32 v57, v30
	v_mov_b32_e32 v30, v29
	v_pk_add_f32 v[28:29], v[52:53], v[54:55]
	s_nop 0
	v_pk_add_f32 v[28:29], v[50:51], v[28:29]
	s_nop 0
	v_add_f32_e32 v28, v28, v29
	s_nop 1
	v_add_f32_dpp v28, v28, v28 quad_perm:[1,0,3,2] row_mask:0xf bank_mask:0xf bound_ctrl:1
	s_nop 1
	v_add_f32_dpp v28, v28, v28 quad_perm:[2,3,0,1] row_mask:0xf bank_mask:0xf bound_ctrl:1
	s_nop 1
	v_add_f32_dpp v28, v28, v28 row_half_mirror row_mask:0xf bank_mask:0xf bound_ctrl:1
	s_nop 1
	v_add_f32_dpp v28, v28, v28 row_mirror row_mask:0xf bank_mask:0xf bound_ctrl:1
	s_nop 1
	v_add_f32_dpp v28, v28, v28 row_bcast:15 row_mask:0xf bank_mask:0xf bound_ctrl:1
	s_nop 1
	v_add_f32_dpp v28, v28, v28 row_bcast:31 row_mask:0xf bank_mask:0xf bound_ctrl:1
	s_nop 0
	v_readlane_b32 s4, v28, 63
	s_nop 1
	v_mul_f32_e32 v50, s4, v229
	v_pk_add_f32 v[52:53], v[14:15], v[50:51] op_sel_hi:[1,0] neg_lo:[0,1] neg_hi:[0,1]
	v_pk_add_f32 v[58:59], v[22:23], v[50:51] op_sel_hi:[1,0] neg_lo:[0,1] neg_hi:[0,1]
	v_pk_mul_f32 v[54:55], v[52:53], v[52:53]
	v_pk_mul_f32 v[60:61], v[58:59], v[58:59]
	v_pk_add_f32 v[62:63], v[16:17], v[50:51] op_sel_hi:[1,0] neg_lo:[0,1] neg_hi:[0,1]
	v_add_f32_e32 v54, v54, v60
	v_add_f32_e32 v54, v55, v54
	v_pk_mul_f32 v[64:65], v[62:63], v[62:63]
	v_pk_add_f32 v[66:67], v[24:25], v[50:51] op_sel_hi:[1,0] neg_lo:[0,1] neg_hi:[0,1]
	v_add_f32_e32 v54, v61, v54
	v_pk_mul_f32 v[68:69], v[66:67], v[66:67]
	v_add_f32_e32 v54, v64, v54
	v_add_f32_e32 v54, v68, v54
	v_pk_add_f32 v[24:25], v[10:11], v[50:51] op_sel_hi:[1,0] neg_lo:[0,1] neg_hi:[0,1]
	v_add_f32_e32 v54, v65, v54
	v_pk_mul_f32 v[70:71], v[24:25], v[24:25]
	v_pk_add_f32 v[28:29], v[18:19], v[50:51] op_sel_hi:[1,0] neg_lo:[0,1] neg_hi:[0,1]
	v_add_f32_e32 v54, v69, v54
	v_pk_mul_f32 v[92:93], v[28:29], v[28:29]
	v_add_f32_e32 v54, v70, v54
	v_add_f32_e32 v54, v92, v54
	v_pk_add_f32 v[22:23], v[12:13], v[50:51] op_sel_hi:[1,0] neg_lo:[0,1] neg_hi:[0,1]
	v_add_f32_e32 v54, v71, v54
	v_pk_mul_f32 v[94:95], v[22:23], v[22:23]
	v_pk_add_f32 v[26:27], v[26:27], v[50:51] op_sel_hi:[1,0] neg_lo:[0,1] neg_hi:[0,1]
	v_add_f32_e32 v54, v93, v54
	v_pk_mul_f32 v[96:97], v[26:27], v[26:27]
	v_add_f32_e32 v54, v94, v54
	v_add_f32_e32 v54, v96, v54
	v_pk_add_f32 v[18:19], v[6:7], v[50:51] op_sel_hi:[1,0] neg_lo:[0,1] neg_hi:[0,1]
	v_add_f32_e32 v54, v95, v54
	v_pk_mul_f32 v[98:99], v[18:19], v[18:19]
	v_pk_add_f32 v[20:21], v[20:21], v[50:51] op_sel_hi:[1,0] neg_lo:[0,1] neg_hi:[0,1]
	v_add_f32_e32 v54, v97, v54
	v_pk_mul_f32 v[100:101], v[20:21], v[20:21]
	v_add_f32_e32 v54, v98, v54
	v_add_f32_e32 v54, v100, v54
	v_pk_add_f32 v[14:15], v[8:9], v[50:51] op_sel_hi:[1,0] neg_lo:[0,1] neg_hi:[0,1]
	v_add_f32_e32 v54, v99, v54
	v_pk_mul_f32 v[8:9], v[14:15], v[14:15]
	v_pk_add_f32 v[16:17], v[48:49], v[50:51] op_sel_hi:[1,0] neg_lo:[0,1] neg_hi:[0,1]
	v_add_f32_e32 v54, v101, v54
	v_pk_mul_f32 v[48:49], v[16:17], v[16:17]
	v_add_f32_e32 v8, v8, v54
	v_add_f32_e32 v8, v48, v8
	v_pk_add_f32 v[10:11], v[2:3], v[50:51] op_sel_hi:[1,0] neg_lo:[0,1] neg_hi:[0,1]
	v_add_f32_e32 v8, v9, v8
	v_pk_mul_f32 v[2:3], v[10:11], v[10:11]
	v_pk_add_f32 v[12:13], v[36:37], v[50:51] op_sel_hi:[1,0] neg_lo:[0,1] neg_hi:[0,1]
	v_add_f32_e32 v8, v49, v8
	v_pk_mul_f32 v[36:37], v[12:13], v[12:13]
	v_add_f32_e32 v2, v2, v8
	v_pk_add_f32 v[4:5], v[4:5], v[50:51] op_sel_hi:[1,0] neg_lo:[0,1] neg_hi:[0,1]
	v_pk_add_f32 v[6:7], v[46:47], v[50:51] op_sel_hi:[1,0] neg_lo:[0,1] neg_hi:[0,1]
	v_add_f32_e32 v2, v36, v2
	v_mov_b32_e32 v46, v6
	v_mov_b32_e32 v47, v4
	v_add_f32_e32 v2, v3, v2
	v_pk_mul_f32 v[46:47], v[46:47], v[46:47]
	v_add_f32_e32 v2, v37, v2
	v_mov_b32_e32 v50, v7
	v_mov_b32_e32 v51, v5
	v_add_f32_e32 v2, v47, v2
	v_pk_mul_f32 v[50:51], v[50:51], v[50:51]
	v_add_f32_e32 v2, v46, v2
	v_add_f32_e32 v2, v51, v2
	v_add_f32_e32 v2, v50, v2
	s_nop 1
	v_add_f32_dpp v2, v2, v2 quad_perm:[1,0,3,2] row_mask:0xf bank_mask:0xf bound_ctrl:1
	s_nop 1
	v_add_f32_dpp v2, v2, v2 quad_perm:[2,3,0,1] row_mask:0xf bank_mask:0xf bound_ctrl:1
	s_nop 1
	v_add_f32_dpp v2, v2, v2 row_half_mirror row_mask:0xf bank_mask:0xf bound_ctrl:1
	s_nop 1
	v_add_f32_dpp v2, v2, v2 row_mirror row_mask:0xf bank_mask:0xf bound_ctrl:1
	s_nop 1
	v_add_f32_dpp v2, v2, v2 row_bcast:15 row_mask:0xf bank_mask:0xf bound_ctrl:1
	s_nop 1
	v_add_f32_dpp v2, v2, v2 row_bcast:31 row_mask:0xf bank_mask:0xf bound_ctrl:1
	s_nop 0
	v_readlane_b32 s4, v2, 63
	s_nop 1
	v_fma_f32 v2, s4, v229, v214
	v_mul_f32_e32 v3, 0x4b800000, v2
	v_cmp_gt_f32_e32 vcc, s70, v2
	s_nop 1
	v_cndmask_b32_e32 v2, v2, v3, vcc
	v_rsq_f32_e32 v8, v2
	s_waitcnt vmcnt(0)
	v_mov_b32_e32 v2, v32
	v_mov_b32_e32 v3, v34
	v_mov_b32_e32 v34, v33
	v_mul_f32_e32 v9, 0x45800000, v8
	v_cndmask_b32_e32 v8, v8, v9, vcc
	v_pk_mul_f32 v[32:33], v[52:53], v[8:9] op_sel_hi:[1,0]
	v_pk_mul_f32 v[46:47], v[58:59], v[8:9] op_sel_hi:[1,0]
	v_pk_fma_f32 v[36:37], v[56:57], v[32:33], v[2:3]
	v_pk_fma_f32 v[30:31], v[30:31], v[46:47], v[34:35]
	v_pk_mul_f32 v[2:3], v[62:63], v[8:9] op_sel_hi:[1,0]
	v_mov_b32_e32 v32, v38
	v_mov_b32_e32 v33, v40
	v_pk_mul_f32 v[46:47], v[66:67], v[8:9] op_sel_hi:[1,0]
	v_mov_b32_e32 v40, v39
	v_mov_b32_e32 v34, v42
	v_mov_b32_e32 v35, v44
	v_mov_b32_e32 v44, v43
	v_pk_fma_f32 v[34:35], v[2:3], v[32:33], v[34:35]
	v_pk_fma_f32 v[32:33], v[46:47], v[40:41], v[44:45]
	s_and_b64 vcc, exec, s[88:89]
	s_cbranch_vccz .LBB0_1264
	v_lshl_add_u64 v[2:3], v[0:1], 0, v[176:177]
	v_mov_b32_e32 v38, v36
	v_mov_b32_e32 v39, v30
	v_mov_b32_e32 v40, v37
	v_mov_b32_e32 v41, v31
	global_store_dwordx4 v[2:3], v[38:41], off
	s_nop 1
	v_mov_b32_e32 v38, v34
	v_mov_b32_e32 v39, v32
	v_mov_b32_e32 v40, v35
	v_mov_b32_e32 v41, v33
	global_store_dwordx4 v[2:3], v[38:41], off offset:16

	.amdhsa_kernel _Z4mega6Params
		.amdhsa_group_segment_fixed_size 16
		.amdhsa_private_segment_fixed_size 0
		.amdhsa_kernarg_size 536
		.amdhsa_user_sgpr_count 2
		.amdhsa_user_sgpr_dispatch_ptr 0
		.amdhsa_user_sgpr_queue_ptr 0
		.amdhsa_user_sgpr_kernarg_segment_ptr 1
		.amdhsa_user_sgpr_dispatch_id 0
		.amdhsa_user_sgpr_kernarg_preload_length 0
		.amdhsa_user_sgpr_kernarg_preload_offset 0
		.amdhsa_user_sgpr_private_segment_size 0
		.amdhsa_uses_dynamic_stack 0
		.amdhsa_enable_private_segment 0
		.amdhsa_system_sgpr_workgroup_id_x 1
		.amdhsa_system_sgpr_workgroup_id_y 0
		.amdhsa_system_sgpr_workgroup_id_z 0
		.amdhsa_system_sgpr_workgroup_info 0
		.amdhsa_system_vgpr_workitem_id 2
		.amdhsa_next_free_vgpr 255
		.amdhsa_next_free_sgpr 102
		.amdhsa_accum_offset 256
		.amdhsa_reserve_vcc 1
		.amdhsa_float_round_mode_32 0
		.amdhsa_float_round_mode_16_64 0
		.amdhsa_float_denorm_mode_32 3
		.amdhsa_float_denorm_mode_16_64 3
		.amdhsa_dx10_clamp 1
		.amdhsa_ieee_mode 1
		.amdhsa_fp16_overflow 0
		.amdhsa_tg_split 0
		.amdhsa_exception_fp_ieee_invalid_op 0
		.amdhsa_exception_fp_denorm_src 0
		.amdhsa_exception_fp_ieee_div_zero 0
		.amdhsa_exception_fp_ieee_overflow 0
		.amdhsa_exception_fp_ieee_underflow 0
		.amdhsa_exception_fp_ieee_inexact 0
		.amdhsa_exception_int_div_zero 0
	.end_amdhsa_kernel

amdhsa.kernels:
  - .agpr_count:     0
    .args:
      - .offset:         0
        .size:           280
        .value_kind:     by_value
      - .offset:         280
        .size:           4
        .value_kind:     hidden_block_count_x
      - .offset:         284
        .size:           4
        .value_kind:     hidden_block_count_y
      - .offset:         288
        .size:           4
        .value_kind:     hidden_block_count_z
      - .offset:         292
        .size:           2
        .value_kind:     hidden_group_size_x
      - .offset:         294
        .size:           2
        .value_kind:     hidden_group_size_y
      - .offset:         296
        .size:           2
        .value_kind:     hidden_group_size_z
      - .offset:         298
        .size:           2
        .value_kind:     hidden_remainder_x
      - .offset:         300
        .size:           2
        .value_kind:     hidden_remainder_y
      - .offset:         302
        .size:           2
        .value_kind:     hidden_remainder_z
      - .offset:         320
        .size:           8
        .value_kind:     hidden_global_offset_x
      - .offset:         328
        .size:           8
        .value_kind:     hidden_global_offset_y
      - .offset:         336
        .size:           8
        .value_kind:     hidden_global_offset_z
      - .offset:         344
        .size:           2
        .value_kind:     hidden_grid_dims
      - .offset:         368
        .size:           8
        .value_kind:     hidden_multigrid_sync_arg
      - .offset:         400
        .size:           4
        .value_kind:     hidden_dynamic_lds_size
    .group_segment_fixed_size: 16
    .kernarg_segment_align: 8
    .kernarg_segment_size: 536
    .language:       OpenCL C
    .language_version:
      - 2
      - 0
    .max_flat_workgroup_size: 512
    .name:           _Z4mega6Params
    .private_segment_fixed_size: 0
    .sgpr_count:     108
    .sgpr_spill_count: 143
    .symbol:         _Z4mega6Params.kd
    .uniform_work_group_size: 1
    .uses_dynamic_stack: false
    .vgpr_count:     255
    .vgpr_spill_count: 0
    .wavefront_size: 64
